# qk-prep row loop: touch the next row's lines (row + rope) one iteration ahead so its loads hit in the vector L1
# speedup vs baseline: 1.0045x; 1.0045x over previous
.LBB0_341:
	v_cmp_gt_u32_e64 s[44:45], 64, v11
	s_and_b64 s[24:25], s[96:97], s[44:45]
	v_cmp_lt_u32_e64 s[42:43], 63, v11
	s_xor_b64 s[34:35], s[24:25], -1
	s_and_saveexec_b64 s[24:25], s[34:35]
	s_cbranch_execz .LBB0_340
	v_and_b32_e32 v24, 63, v11
	s_andn2_b64 vcc, exec, s[26:27]
	s_mov_b64 s[34:35], -1
	s_cbranch_vccnz .LBB0_346
	v_cndmask_b32_e64 v6, v54, v52, s[44:45]
	v_cndmask_b32_e64 v7, v55, v53, s[44:45]
	v_readlane_b32 s34, v252, 36
	v_readlane_b32 s35, v252, 37
	v_or_b32_e32 v25, s75, v24
	v_and_b32_e32 v4, 0xfffffe00, v32
	v_mov_b64_e32 v[2:3], s[34:35]
	s_movk_i32 s34, 0xc00
	v_mad_u64_u32 v[2:3], s[34:35], v25, s34, v[2:3]
	v_ashrrev_i32_e32 v5, 31, v4
	v_lshl_add_u64 v[2:3], v[4:5], 1, v[2:3]
	v_lshlrev_b32_e32 v8, 1, v10
	v_mov_b32_e32 v9, v1
	v_lshl_add_u64 v[2:3], v[2:3], 0, v[0:1]
	v_lshl_add_u64 v[2:3], v[2:3], 0, v[8:9]
	v_add_co_u32_e32 v60, vcc, 0x3000, v2
	v_addc_co_u32_e32 v61, vcc, 0, v3, vcc
	global_load_dwordx4 v[2:5], v[2:3], off
	v_lshlrev_b32_e32 v8, 2, v10
	v_lshlrev_b32_e32 v25, 7, v25
	v_mov_b32_e32 v31, v1
	v_and_b32_e32 v30, 0x7ff80, v25
	v_lshl_add_u64 v[38:39], v[12:13], 0, v[30:31]
	v_mov_b32_e32 v62, v38
	v_mov_b32_e32 v63, v39
	v_lshl_add_u64 v[30:31], v[14:15], 0, v[30:31]
	v_cmp_lt_i32_e32 vcc, v227, v221
	s_nop 0
	v_lshl_add_u64 v[6:7], s[40:41], 2, v[6:7]
	v_lshl_add_u64 v[26:27], v[6:7], 0, v[8:9]
	global_load_dwordx4 v[6:9], v[26:27], off offset:16
	s_nop 0
	global_load_dwordx4 v[26:29], v[26:27], off
	s_nop 0
	global_load_dwordx4 v[34:37], v[30:31], off
	s_nop 0
	global_load_dwordx4 v[38:41], v[38:39], off
	global_load_dwordx4 v[66:69], v[60:61], off
	global_load_dwordx4 v[70:73], v[30:31], off offset:512
	global_load_dwordx4 v[74:77], v[62:63], off offset:512
	s_waitcnt vmcnt(7)
	v_cndmask_b32_e32 v25, v220, v227, vcc
	v_lshlrev_b32_e32 v25, 2, v25
	v_cmp_lt_i32_e32 vcc, v226, v221
	v_lshlrev_b32_e32 v30, 16, v2
	v_and_b32_e32 v31, 0xffff0000, v2
	v_lshlrev_b32_e32 v2, 16, v3
	v_and_b32_e32 v3, 0xffff0000, v3
	v_pk_mul_f32 v[46:47], v[30:31], v[30:31]
	v_pk_mul_f32 v[48:49], v[2:3], v[2:3]
	v_add_f32_e32 v33, v46, v47
	v_lshlrev_b32_e32 v42, 16, v4
	v_and_b32_e32 v43, 0xffff0000, v4
	v_add_f32_e32 v33, v33, v48
	v_pk_mul_f32 v[50:51], v[42:43], v[42:43]
	v_add_f32_e32 v33, v49, v33
	v_lshlrev_b32_e32 v4, 16, v5
	v_and_b32_e32 v5, 0xffff0000, v5
	v_add_f32_e32 v33, v50, v33
	v_pk_mul_f32 v[44:45], v[4:5], v[4:5]
	v_add_f32_e32 v33, v51, v33
	v_add_f32_e32 v33, v44, v33
	v_add_f32_e32 v33, v45, v33
	ds_bpermute_b32 v25, v25, v33
	v_cndmask_b32_e32 v44, v220, v226, vcc
	v_lshlrev_b32_e32 v44, 2, v44
	v_cmp_lt_i32_e32 vcc, v235, v221
	s_waitcnt lgkmcnt(0)
	v_add_f32_e32 v25, v33, v25
	ds_bpermute_b32 v33, v44, v25
	v_cndmask_b32_e32 v44, v220, v235, vcc
	v_lshlrev_b32_e32 v44, 2, v44
	s_waitcnt lgkmcnt(0)
	v_add_f32_e32 v25, v25, v33
	ds_bpermute_b32 v33, v44, v25
	s_waitcnt lgkmcnt(0)
	v_add_f32_e32 v25, v25, v33
	v_fmamk_f32 v25, v25, 0x3c800000, v187
	v_mul_f32_e32 v33, 0x4b800000, v25
	v_cmp_gt_f32_e32 vcc, s82, v25
	s_nop 1
	v_cndmask_b32_e32 v25, v25, v33, vcc
	v_rsq_f32_e32 v25, v25
	s_nop 0
	v_mul_f32_e32 v33, 0x45800000, v25
	v_cndmask_b32_e32 v44, v25, v33, vcc
	v_pk_mul_f32 v[30:31], v[44:45], v[30:31] op_sel_hi:[0,1]
	v_pk_mul_f32 v[2:3], v[44:45], v[2:3] op_sel_hi:[0,1]
	v_pk_mul_f32 v[42:43], v[44:45], v[42:43] op_sel_hi:[0,1]
	v_pk_mul_f32 v[4:5], v[44:45], v[4:5] op_sel_hi:[0,1]
	s_waitcnt vmcnt(5)
	v_pk_mul_f32 v[26:27], v[26:27], v[30:31]
	v_pk_mul_f32 v[28:29], v[28:29], v[2:3]
	v_pk_mul_f32 v[30:31], v[6:7], v[42:43]
	v_pk_mul_f32 v[42:43], v[8:9], v[4:5]
	s_waitcnt vmcnt(4)
	v_pk_mul_f32 v[44:45], v[34:35], v[26:27] op_sel:[0,1] op_sel_hi:[0,0]
	v_pk_mul_f32 v[6:7], v[34:35], v[28:29] op_sel:[1,1] op_sel_hi:[1,0]
	v_pk_mul_f32 v[8:9], v[30:31], v[36:37] op_sel:[1,0] op_sel_hi:[0,0]
	s_waitcnt vmcnt(3)
	v_pk_mul_f32 v[46:47], v[38:39], v[26:27] op_sel_hi:[0,1]
	v_mov_b32_e32 v36, v41
	v_mul_f32_e32 v34, v37, v43
	v_mul_f32_e32 v48, v41, v43
	v_pk_fma_f32 v[2:3], v[38:39], v[26:27], v[44:45] op_sel_hi:[0,1,1]
	v_pk_fma_f32 v[4:5], v[38:39], v[28:29], v[6:7] op_sel:[1,0,0] neg_lo:[0,0,1] neg_hi:[0,0,1]
	v_pk_fma_f32 v[26:27], v[38:39], v[28:29], v[6:7] op_sel:[1,0,0]
	v_pk_fma_f32 v[6:7], v[40:41], v[30:31], v[8:9] op_sel_hi:[0,1,1] neg_lo:[0,0,1] neg_hi:[0,0,1]
	v_pk_fma_f32 v[28:29], v[40:41], v[30:31], v[8:9] op_sel_hi:[0,1,1]
	v_mov_b32_e32 v40, v37
	v_pk_fma_f32 v[8:9], v[36:37], v[42:43], v[34:35] op_sel_hi:[1,1,0] neg_lo:[0,0,1] neg_hi:[0,0,1]
	v_pk_fma_f32 v[30:31], v[40:41], v[42:43], v[48:49] op_sel_hi:[1,1,0]
	v_sub_f32_e32 v2, v46, v44
	s_cbranch_execz .LBB0_347

.LBB0_445:
	v_cmp_gt_u32_e64 s[44:45], 64, v11
	s_and_b64 s[28:29], s[20:21], s[44:45]
	v_cmp_lt_u32_e64 s[42:43], 63, v11
	s_xor_b64 s[34:35], s[28:29], -1
	s_and_saveexec_b64 s[28:29], s[34:35]
	s_cbranch_execz .LBB0_444
	v_and_b32_e32 v22, 63, v11
	s_andn2_b64 vcc, exec, s[4:5]
	s_mov_b64 s[34:35], -1
	s_cbranch_vccnz .LBB0_450
	v_cndmask_b32_e64 v6, v54, v52, s[44:45]
	v_cndmask_b32_e64 v7, v55, v53, s[44:45]
	v_readlane_b32 s34, v252, 36
	v_readlane_b32 s35, v252, 37
	v_or_b32_e32 v5, s76, v22
	v_and_b32_e32 v4, 0xfffffe00, v24
	v_mov_b64_e32 v[2:3], s[34:35]
	s_movk_i32 s34, 0xc00
	v_mad_u64_u32 v[2:3], s[34:35], v5, s34, v[2:3]
	v_ashrrev_i32_e32 v5, 31, v4
	v_lshl_add_u64 v[2:3], v[4:5], 1, v[2:3]
	v_lshlrev_b32_e32 v8, 1, v10
	v_mov_b32_e32 v9, v1
	v_lshl_add_u64 v[2:3], v[2:3], 0, v[0:1]
	v_lshl_add_u64 v[2:3], v[2:3], 0, v[8:9]
	v_add_co_u32_e32 v60, vcc, 0x3000, v2
	v_addc_co_u32_e32 v61, vcc, 0, v3, vcc
	global_load_dwordx4 v[2:5], v[2:3], off
	v_lshlrev_b32_e32 v8, 2, v10
	v_cmp_lt_i32_e32 vcc, v227, v221
	s_nop 0
	v_lshl_add_u64 v[6:7], s[12:13], 2, v[6:7]
	v_lshl_add_u64 v[26:27], v[6:7], 0, v[8:9]
	global_load_dwordx4 v[6:9], v[26:27], off
	s_nop 0
	global_load_dwordx4 v[26:29], v[26:27], off offset:16
	global_load_dwordx4 v[66:69], v[60:61], off
	s_waitcnt vmcnt(3)
	v_cndmask_b32_e32 v23, v220, v227, vcc
	v_lshlrev_b32_e32 v23, 2, v23
	v_cmp_lt_i32_e32 vcc, v226, v221
	v_lshlrev_b32_e32 v30, 16, v2
	v_and_b32_e32 v31, 0xffff0000, v2
	v_lshlrev_b32_e32 v2, 16, v3
	v_and_b32_e32 v3, 0xffff0000, v3
	v_pk_mul_f32 v[36:37], v[30:31], v[30:31]
	v_pk_mul_f32 v[38:39], v[2:3], v[2:3]
	v_add_f32_e32 v25, v36, v37
	v_lshlrev_b32_e32 v32, 16, v4
	v_and_b32_e32 v33, 0xffff0000, v4
	v_add_f32_e32 v25, v25, v38
	v_pk_mul_f32 v[40:41], v[32:33], v[32:33]
	v_add_f32_e32 v25, v39, v25
	v_lshlrev_b32_e32 v35, 16, v5
	v_and_b32_e32 v34, 0xffff0000, v5
	v_add_f32_e32 v25, v40, v25
	v_pk_mul_f32 v[4:5], v[34:35], v[34:35]
	v_add_f32_e32 v25, v41, v25
	v_add_f32_e32 v5, v5, v25
	v_add_f32_e32 v4, v4, v5
	ds_bpermute_b32 v5, v23, v4
	v_cndmask_b32_e32 v23, v220, v226, vcc
	v_lshlrev_b32_e32 v23, 2, v23
	v_cmp_lt_i32_e32 vcc, v235, v221
	s_waitcnt lgkmcnt(0)
	v_add_f32_e32 v4, v4, v5
	ds_bpermute_b32 v5, v23, v4
	v_cndmask_b32_e32 v23, v220, v235, vcc
	v_lshlrev_b32_e32 v23, 2, v23
	s_waitcnt lgkmcnt(0)
	v_add_f32_e32 v4, v4, v5
	ds_bpermute_b32 v5, v23, v4
	s_waitcnt lgkmcnt(0)
	v_add_f32_e32 v4, v4, v5
	v_fmamk_f32 v4, v4, 0x3c800000, v187
	v_mul_f32_e32 v5, 0x4b800000, v4
	v_cmp_gt_f32_e32 vcc, s82, v4
	s_nop 1
	v_cndmask_b32_e32 v4, v4, v5, vcc
	v_rsq_f32_e32 v4, v4
	s_nop 0
	v_mul_f32_e32 v5, 0x45800000, v4
	v_cndmask_b32_e32 v4, v4, v5, vcc
	v_pk_mul_f32 v[30:31], v[4:5], v[30:31] op_sel_hi:[0,1]
	v_pk_mul_f32 v[36:37], v[4:5], v[2:3] op_sel_hi:[0,1]
	v_pk_mul_f32 v[32:33], v[4:5], v[32:33] op_sel_hi:[0,1]
	v_pk_mul_f32 v[34:35], v[4:5], v[34:35] op_sel_hi:[0,1]
	s_waitcnt vmcnt(2)
	v_pk_mul_f32 v[2:3], v[6:7], v[30:31]
	v_pk_mul_f32 v[4:5], v[8:9], v[36:37]
	s_waitcnt vmcnt(1)
	v_pk_mul_f32 v[6:7], v[26:27], v[32:33]
	v_pk_mul_f32 v[8:9], v[28:29], v[34:35] op_sel:[0,1] op_sel_hi:[1,0]
	s_cbranch_execz .LBB0_451

.LBB0_449:
	v_mov_b32_e32 v23, v1
	v_lshl_add_u64 v[30:31], v[12:13], 0, v[22:23]
	v_add_u32_e32 v22, s26, v22
	v_ashrrev_i32_e32 v23, 31, v22
	v_lshlrev_b64 v[30:31], 7, v[30:31]
	v_lshlrev_b64 v[22:23], 11, v[22:23]
	s_waitcnt vmcnt(1)
	v_cvt_pk_bf16_f32 v26, v2, v3
	v_cvt_pk_bf16_f32 v27, v4, v5
	v_cvt_pk_bf16_f32 v28, v6, v7
	v_cvt_pk_bf16_f32 v29, v8, v9
	v_lshl_add_u64 v[30:31], v[14:15], 0, v[30:31]
	v_lshl_add_u64 v[22:23], v[20:21], 0, v[22:23]
	global_store_dwordx4 v[30:31], v[26:29], off
	global_store_dwordx4 v[22:23], v[2:5], off
	global_store_dwordx4 v[22:23], v[6:9], off offset:16
	s_andn2_saveexec_b64 s[34:35], s[42:43]
	s_cbranch_execz .LBB0_444
	s_branch .LBB0_453
